# also P2->P3: 5-tile workgroups leave seam 2 once P2 round 3 is complete on their XCD and run P3 tiles of the complete row panels (P3 assignment swapped between rank halves)
# baseline (speedup 1.0000x reference)
.LBB0_192:
	s_cmp_lg_u32 s79, 4
	s_cbranch_scc1 .Lp2_noprog
	v_readfirstlane_b32 s10, v199
	s_nop 3
	s_cmp_lg_u32 s10, 0
	s_cbranch_scc1 .Lp2_noprog
	v_mov_b32_e32 v144, 0x20040
	ds_read_b32 v145, v144 offset:8
	ds_read_b32 v155, v144 offset:16
	s_lshl_b32 s10, s33, 7
	s_add_u32 s10, s10, 0x3600
	s_waitcnt lgkmcnt(0)
	v_cmp_ne_u32_e32 vcc, 0, v155
	s_cbranch_vccz .Lp2_noprog
	v_lshl_add_u32 v145, v145, 2, s10
	v_mov_b32_e32 v144, 3
	global_store_dword v145, v144, s[12:13]

.LBB0_262:
	s_cmp_gt_i32 s69, 3
	s_cselect_b64 s[0:1], -1, 0
	s_and_b64 s[2:3], s[4:5], s[0:1]
	s_andn2_b64 vcc, exec, s[2:3]
	s_cbranch_vccnz .LBB0_316
	s_waitcnt vmcnt(0)
	s_waitcnt vmcnt(0) lgkmcnt(0)
	s_barrier
	v_mov_b32_e32 v0, 0x20040
	ds_read_b32 v2, v0
	ds_read_b32 v3, v0 offset:16
	ds_read_b32 v5, v0 offset:8
	s_lshl_b32 s2, s33, 7
	s_add_u32 s2, s2, 0x3600
	v_lshl_add_u32 v0, v199, 2, s2
	v_mov_b32_e32 v6, 4
	v_mov_b32_e32 v7, 4
	s_waitcnt lgkmcnt(0)
	v_cmp_eq_u32_e32 vcc, 0, v3
	s_cbranch_vccnz .Lxl_orig_2
	v_cmp_lt_u32_e32 vcc, 32, v2
	s_cbranch_vccnz .Lxl_orig_2
	v_lshl_add_u32 v1, v5, 2, s2
	v_cmp_gt_u32_e32 vcc, 16, v5
	s_nop 1
	v_cndmask_b32_e64 v7, 3, 4, vcc
	v_cmp_lt_u32_e32 vcc, v199, v2
	s_and_saveexec_b64 s[4:5], vcc
	s_cbranch_execz .LBB0_315
	v_cmp_eq_u32_e32 vcc, 0, v199
	s_and_saveexec_b64 s[2:3], vcc
	global_store_dword v1, v6, s[92:93]
	s_mov_b64 exec, s[2:3]
	buffer_inv sc1
	s_mov_b32 s2, 0x20000

.LBB0_316:
	s_xor_b32 s38, s38, 0x80
	s_cmp_lt_i32 s68, 4
	s_cselect_b64 s[2:3], -1, 0
	s_add_u32 s4, s30, 0xfd00000
	s_addc_u32 s5, s31, 0
	v_writelane_b32 v255, s4, 20
	s_and_b64 s[8:9], s[2:3], s[0:1]
	s_andn2_b64 vcc, exec, s[8:9]
	v_writelane_b32 v255, s5, 21
	s_cbranch_vccnz .LBB0_363
	s_cmpk_lt_i32 s38, 0x100
	s_cselect_b64 s[0:1], -1, 0
	s_cmpk_gt_i32 s38, 0xff
	v_readfirstlane_b32 s6, v199
	s_cbranch_scc1 .LBB0_323
	s_ashr_i32 s2, s38, 31
	s_lshr_b32 s2, s2, 29
	s_add_i32 s2, s38, s2
	s_and_b32 s3, s2, -8
	s_sub_i32 s3, s38, s3
	s_cmp_gt_i32 s3, -1
	s_cbranch_scc0 .LBB0_320
	s_lshl_b32 s7, s3, 5
	s_cbranch_execz .LBB0_321
	s_branch .LBB0_322

.LBB0_363:
	s_xor_b32 s38, s38, 0x80
	s_cmp_gt_i32 s69, 4
	s_cselect_b64 s[0:1], -1, 0
	s_and_b64 s[2:3], s[8:9], s[0:1]
	s_andn2_b64 vcc, exec, s[2:3]
	s_cbranch_vccnz .LBB0_417
	s_waitcnt vmcnt(0)
	s_waitcnt vmcnt(0) lgkmcnt(0)
	s_barrier
	v_mov_b32_e32 v0, 0x20040
	ds_read_b32 v2, v0
	ds_read_b32 v3, v0 offset:16
	ds_read_b32 v5, v0 offset:8
	s_lshl_b32 s2, s33, 7
	s_add_u32 s2, s2, 0x3600
	v_lshl_add_u32 v0, v199, 2, s2
	v_mov_b32_e32 v6, 6
	v_mov_b32_e32 v7, 6
	s_waitcnt lgkmcnt(0)
	v_cmp_eq_u32_e32 vcc, 0, v3
	s_cbranch_vccnz .Lxl_orig_3
	v_cmp_lt_u32_e32 vcc, 32, v2
	s_cbranch_vccnz .Lxl_orig_3
	v_lshl_add_u32 v1, v5, 2, s2
	v_cmp_lt_u32_e32 vcc, v199, v2
	s_and_saveexec_b64 s[4:5], vcc
	s_cbranch_execz .LBB0_416
	v_cmp_eq_u32_e32 vcc, 0, v199
	s_and_saveexec_b64 s[2:3], vcc
	global_store_dword v1, v6, s[92:93]
	s_mov_b64 exec, s[2:3]
	buffer_inv sc1
	s_mov_b32 s2, 0x20000
